# pipelined V-transpose loop in attn prep; removed grid barrier between out-proj GEMM and gate GEMM (same tile to workgroup mapping, Y tile is workgroup-local)
# speedup vs baseline: 1.0004x; 1.0004x over previous
; __device__ __forceinline__ void phase_attn_prep(KP P, int l_, unsigned char* shm) {
;     ...
;     {
;         u16* vT = (u16*)(P->ws + WS_LO);
;         u16* tile = (u16*)shm;
;         const int ts = tid_ >> 3, tc = tid_ & 7;
;         const int te = tid_ >> 2, tq = tid_ & 3;
;         for (int it = blockIdx.x; it < 4096; it += gridDim.x) {
;             const int bh = it >> 5, sb = it & 31, b = bh >> 2, h = bh & 3;
;             const u16* src = pA + ((size_t)b * SEQ + sb * 64 + ts) * 1536 + 1024 + h * 128 + tc * 16;
;             const uint4 a0 = *(const uint4*)src, a1 = *(const uint4*)(src + 8);
;             *(uint4*)(tile + ts * 136 + tc * 16) = a0; *(uint4*)(tile + ts * 136 + tc * 16 + 8) = a1;
;             __syncthreads();
;             unsigned w[8];
; #pragma unroll
;             for (int j = 0; j < 8; ++j) w[j] = (unsigned)tile[(tq * 16 + 2 * j) * 136 + te] | ((unsigned)tile[(tq * 16 + 2 * j + 1) * 136 + te] << 16);
;             u16* dst = vT + ((size_t)bh * 128 + te) * SEQ + sb * 64 + tq * 16;
;             uint4 o0, o1; o0.x = w[0]; o0.y = w[1]; o0.z = w[2]; o0.w = w[3]; o1.x = w[4]; o1.y = w[5]; o1.z = w[6]; o1.w = w[7];
;             *(uint4*)dst = o0; *(uint4*)(dst + 8) = o1;
;             __syncthreads();
;         }
;     }
.LBB0_2591:
	s_or_b64 exec, exec, s[8:9]
	v_readlane_b32 s0, v254, 6
	v_readlane_b32 s1, v254, 7
	s_andn2_b64 vcc, exec, s[0:1]
	s_cbranch_vccnz .LBB0_2594
	v_lshlrev_b32_e32 v3, 4, v58
	v_ashrrev_i32_e32 v0, 3, v58
	v_and_b32_e32 v4, 0x70, v3
	s_movk_i32 s0, 0x110
	v_ashrrev_i32_e32 v2, 2, v58
	v_mul_lo_u32 v6, v0, s0
	v_lshlrev_b32_e32 v7, 1, v4
	v_add3_u32 v8, 0, v6, v7
	v_and_b32_e32 v6, 48, v3
	v_ashrrev_i32_e32 v3, 31, v2
	v_lshlrev_b32_e32 v7, 1, v2
	v_lshlrev_b64 v[2:3], 12, v[2:3]
	v_and_b32_e32 v11, 2, v58
	v_and_b32_e32 v12, 1, v58
	v_lshlrev_b32_e32 v11, 4, v11
	v_lshl_or_b32 v11, v12, 3, v11
	v_mul_u32_u24_e32 v9, 0x88, v11
	v_lshl_add_u64 v[2:3], s[6:7], 0, v[2:3]
	s_mov_b64 s[0:1], 0x2bb00000
	v_lshlrev_b32_e32 v10, 1, v9
	v_ashrrev_i32_e32 v1, 31, v0
	v_lshl_add_u64 v[2:3], v[2:3], 0, s[0:1]
	v_add3_u32 v9, 0, v7, v10
	v_add3_u32 v10, 0, v10, v7
	v_lshlrev_b32_e32 v4, 1, v4
	v_lshlrev_b32_e32 v6, 1, v6
	v_readlane_b32 s8, v254, 25
	s_mov_b32 s9, s2
	s_ashr_i32 s10, s9, 7
	s_ashr_i32 s11, s10, 31
	s_lshl_b64 s[10:11], s[10:11], 11
	s_and_b32 s0, s8, 0x7c0
	s_or_b32 s10, s10, s0
	s_ashr_i32 s6, s9, 5
	v_lshl_add_u64 v[12:13], s[10:11], 0, v[0:1]
	v_mov_b64_e32 v[14:15], s[4:5]
	v_mad_u64_u32 v[14:15], s[10:11], v12, s83, v[14:15]
	s_lshl_b32 s1, s6, 8
	v_mad_i32_i24 v15, v13, s83, v15
	s_and_b32 s52, s1, 0x300
	v_lshl_add_u64 v[12:13], v[14:15], 0, s[52:53]
	v_lshl_add_u64 v[16:17], v[12:13], 0, v[4:5]
	global_load_dwordx4 v[22:25], v[16:17], off offset:2064
	global_load_dwordx4 v[26:29], v[16:17], off offset:2048
	s_waitcnt vmcnt(0)
.LBB0_2593:
	s_ashr_i32 s6, s9, 5
	s_and_b32 s0, s8, 0x7c0
	s_ashr_i32 s7, s6, 31
	s_lshl_b64 s[6:7], s[6:7], 19
	v_lshl_add_u64 v[20:21], v[2:3], 0, s[6:7]
	s_lshl_b32 s52, s0, 1
	v_lshl_add_u64 v[20:21], v[20:21], 0, s[52:53]
	s_add_i32 s9, s9, s44
	s_add_i32 s8, s8, s78
	s_cmpk_gt_i32 s9, 0xfff
	s_cselect_b32 s98, 1, 0
	s_waitcnt vmcnt(2)
	ds_write_b128 v8, v[26:29]
	ds_write_b128 v8, v[22:25] offset:16
	s_cmp_lg_u32 s98, 0
	s_cbranch_scc1 .Lvt_noload
	s_ashr_i32 s10, s9, 7
	s_ashr_i32 s11, s10, 31
	s_lshl_b64 s[10:11], s[10:11], 11
	s_and_b32 s0, s8, 0x7c0
	s_or_b32 s10, s10, s0
	s_ashr_i32 s6, s9, 5
	v_lshl_add_u64 v[12:13], s[10:11], 0, v[0:1]
	v_mov_b64_e32 v[14:15], s[4:5]
	v_mad_u64_u32 v[14:15], s[10:11], v12, s83, v[14:15]
	s_lshl_b32 s1, s6, 8
	v_mad_i32_i24 v15, v13, s83, v15
	s_and_b32 s52, s1, 0x300
	v_lshl_add_u64 v[12:13], v[14:15], 0, s[52:53]
	v_lshl_add_u64 v[16:17], v[12:13], 0, v[4:5]
	global_load_dwordx4 v[22:25], v[16:17], off offset:2064
	global_load_dwordx4 v[26:29], v[16:17], off offset:2048
.Lvt_noload:
	s_waitcnt lgkmcnt(0)
	s_barrier
	ds_read_u16 v30, v9
	ds_read_u16 v31, v10 offset:272
	ds_read_u16 v32, v9 offset:544
	ds_read_u16 v33, v10 offset:816
	ds_read_u16 v34, v9 offset:4352
	ds_read_u16 v35, v10 offset:4624
	ds_read_u16 v36, v9 offset:4896
	ds_read_u16 v37, v10 offset:5168
	ds_read_u16 v38, v9 offset:1088
	ds_read_u16 v39, v10 offset:1360
	ds_read_u16 v40, v9 offset:1632
	ds_read_u16 v41, v10 offset:1904
	ds_read_u16 v42, v9 offset:5440
	ds_read_u16 v43, v10 offset:5712
	ds_read_u16 v44, v9 offset:5984
	ds_read_u16 v45, v10 offset:6256
	s_waitcnt lgkmcnt(0)
	v_lshl_or_b32 v12, v31, 16, v30
	v_lshl_or_b32 v13, v33, 16, v32
	v_lshl_or_b32 v14, v35, 16, v34
	v_lshl_or_b32 v15, v37, 16, v36
	v_lshl_or_b32 v16, v39, 16, v38
	v_lshl_or_b32 v17, v41, 16, v40
	v_lshl_or_b32 v18, v43, 16, v42
	v_lshl_or_b32 v19, v45, 16, v44
	v_mov_b32_e32 v7, v5
	v_lshl_add_u64 v[20:21], v[20:21], 0, v[6:7]
	global_store_dwordx4 v[20:21], v[12:15], off
	global_store_dwordx4 v[20:21], v[16:19], off offset:16
	s_barrier
	s_cmp_eq_u32 s98, 0
	s_cbranch_scc1 .LBB0_2593

; #define PG8_WAIT_V(n) asm volatile("s_waitcnt vmcnt(" #n ")" ::: "memory")
; template <class Epi>
; __device__ __forceinline__ void gemm_phase(LAS unsigned char* lds, const Gemm g, const StaticOrder& S, const Epi& E) {
;     const int tid = ltid(), wid = __builtin_amdgcn_readfirstlane(tid >> 6), lane = tid & 63, wr = wid >> 2, wc = wid & 3, fr = lane & 15, fq = lane >> 4;
;     const int K = g.K, nt = K / BK;
;     unsigned voffA[2], voffB[2];
; #pragma unroll
;     for (int i = 0; i < 2; ++i) { int R, C; stage_rc(tid * 16 + i * 8192, R, C); const int Rb = Epi::PERM ? ((R & ~31) + perm32(R & 31)) : R;
;         voffA[i] = (unsigned)(R * K + C) * 2u; voffB[i] = (unsigned)(Rb * K + C) * 2u; }
;     const size_t kstep = (size_t)(BK * 2);
;     const size_t hstep = (size_t)HALF * K * 2;
;     const size_t tstep = 2 * hstep;
;     const unsigned ldsw = (unsigned)wid * 1024u;
;     const int aoff = lds_byte(wr * 64 + fr, fq * 8), boff = lds_byte(wc * 32 + fr, fq * 8);
;     ...
;     Unit cur, nxt; int ui = 0;
;     if (!S.next(0, cur)) return;
;     f32x4 acc[2][2][4][2];
; #pragma unroll
;     for (int a = 0; a < 2; ++a)
; #pragma unroll
;         for (int b = 0; b < 2; ++b)
; #pragma unroll
;             for (int m = 0; m < 4; ++m)
; #pragma unroll
;                 for (int n = 0; n < 2; ++n) acc[a][b][m][n] = (f32x4){0.f, 0.f, 0.f, 0.f};
;     bf16x8 At[4][2], B0[2][2], B1[2][2];
;     const char* cA = (const char*)g.A + (size_t)cur.pm * tstep; const char* cB = (const char*)g.Bt + (size_t)cur.pn * tstep;
;     PG8_STAGE(PG8_SB(0, 0), cB, voffB); PG8_STAGE(PG8_SA(0, 0), cA, voffA); PG8_STAGE(PG8_SB(0, 1), cB + hstep, voffB); PG8_STAGE(PG8_SA(0, 1), cA + hstep, voffA);
;     if (wr == 1) PG8_BAR;
;     PG8_WAIT_V(4); PG8_BAR;
;     PG8_STAGE(PG8_SB(1, 0), cB + kstep, voffB); PG8_STAGE(PG8_SA(1, 0), cA + kstep, voffA); PG8_STAGE(PG8_SB(1, 1), cB + hstep + kstep, voffB);
;     PG8_WAIT_V(6); PG8_BAR;
; __global__ void __launch_bounds__(512, 2) mega_fwd(Params Parg) {
;     ...
;                     GSYNC();
;                     { KP P = kparams(); const u16* Wl = (const u16*)(P->ws + WS_W) + (size_t)l * W_LAYER;
;                       pg8::Gemm g; g.A = (const u16*)(P->ws + WS_U); g.Bt = Wl + W_G + (size_t)br * 1024 * 1024; g.M = NTOK; g.N = 1024; g.K = 1024;
;                       EpiGate e; e.Z = (u16*)(P->ws + WS_Z); e.Y = (const u16*)(P->ws + WS_P); e.first = (br == 0);
.LBB0_2737:
	v_readlane_b32 s0, v254, 8
	s_mov_b64 s[4:5], s[72:73]
	v_mov_b32_e32 v16, v228
	v_readlane_b32 s1, v254, 9
	s_waitcnt lgkmcnt(0)
	s_barrier
	s_and_b64 vcc, exec, s[0:1]
	v_readfirstlane_b32 s26, v16
	s_cbranch_vccz .LBB0_2837
	v_lshlrev_b32_e32 v0, 4, v16
	v_add_u32_e32 v1, 0x2000, v0
	v_ashrrev_i32_e32 v2, 31, v1
	v_lshrrev_b32_e32 v2, 22, v2
	v_add_u32_e32 v2, v1, v2
	v_ashrrev_i32_e32 v10, 10, v2
	v_mul_i32_i24_e32 v2, 0x400, v10
	v_sub_u32_e32 v1, v1, v2
	v_lshrrev_b32_e32 v2, 4, v1
	v_bitop3_b32 v1, v2, v1, 32 bitop3:0x6c
	v_ashrrev_i32_e32 v2, 31, v1
	v_lshrrev_b32_e32 v2, 26, v2
	v_add_u32_e32 v2, v1, v2
	v_lshlrev_b32_e32 v3, 3, v10
	v_ashrrev_i32_e32 v11, 6, v2
	v_and_b32_e32 v3, -16, v3
	v_add_u32_e32 v3, v11, v3
	v_and_b32_e32 v4, 3, v11
	v_lshrrev_b32_e32 v6, 2, v3
	v_lshlrev_b32_e32 v7, 1, v3
	v_and_b32_e32 v2, 0xc0, v2
	v_and_or_b32 v4, v3, s69, v4
	v_and_b32_e32 v6, 4, v6
	v_and_b32_e32 v7, 24, v7
	v_sub_u32_e32 v1, v1, v2
	v_or3_b32 v4, v4, v6, v7
	v_lshlrev_b32_e32 v6, 5, v10
	v_ashrrev_i16_sdwa v1, v233, sext(v1) dst_sel:DWORD dst_unused:UNUSED_PAD src0_sel:DWORD src1_sel:BYTE_0
	v_and_b32_e32 v6, 32, v6
	v_bfe_i32 v12, v1, 0, 16
	v_add_lshl_u32 v1, v6, v12, 1
	v_lshl_add_u32 v190, v4, 11, v1
	v_lshl_add_u32 v192, v3, 11, v1
	v_bfe_i32 v1, v16, 27, 1
	v_lshrrev_b32_e32 v1, 22, v1
	v_add_u32_e32 v1, v0, v1
	v_and_b32_e32 v1, 0xfffffc00, v1
	v_sub_u32_e32 v0, v0, v1
	v_lshrrev_b32_e32 v1, 4, v0
	s_load_dwordx2 s[4:5], s[4:5], 0xf8
	v_bitop3_b32 v1, v1, v0, 32 bitop3:0x6c
	v_ashrrev_i32_e32 v0, 31, v0
	v_lshrrev_b32_e32 v0, 26, v0
	v_readlane_b32 s0, v254, 59
	v_add_u32_e32 v0, v1, v0
	v_readlane_b32 s1, v254, 60
	v_ashrrev_i32_e32 v13, 6, v0
	v_ashrrev_i32_e32 v0, 31, v16
	s_lshl_b64 s[0:1], s[0:1], 1
	v_lshrrev_b32_e32 v0, 26, v0
	s_waitcnt lgkmcnt(0)
	s_add_u32 s16, s4, s0
	v_add_u32_e32 v0, v16, v0
	s_addc_u32 s17, s5, s1
	v_ashrrev_i32_e32 v14, 6, v0
	s_add_u32 s27, s4, 0x7b00000
	v_readlane_b32 s0, v255, 10
	v_lshlrev_b32_e32 v0, 3, v14
	s_addc_u32 s28, s5, 0
	s_lshl_b32 s52, s0, 10
	v_and_b32_e32 v0, -16, v0
	s_lshl_b64 s[0:1], s[52:53], 11
	v_add_u32_e32 v0, v13, v0
	s_add_u32 s0, s16, s0
	v_and_b32_e32 v2, 3, v13
	v_lshrrev_b32_e32 v3, 2, v0
	v_lshlrev_b32_e32 v4, 1, v0
	s_addc_u32 s1, s17, s1
	v_and_or_b32 v2, v0, s69, v2
	v_and_b32_e32 v3, 4, v3
	v_and_b32_e32 v4, 24, v4
	s_add_u32 s29, s0, 0x2c00000
	v_or3_b32 v2, v2, v3, v4
	v_mul_i32_i24_e32 v4, 64, v13
	s_addc_u32 s30, s1, 0
	s_ashr_i32 s14, s26, 6
	v_sub_u32_e32 v1, v1, v4
	s_ashr_i32 s15, s26, 8
	s_lshl_b32 s31, s14, 10
	v_lshlrev_b32_e32 v3, 5, v14
	v_ashrrev_i16_sdwa v1, v233, sext(v1) dst_sel:DWORD dst_unused:UNUSED_PAD src0_sel:DWORD src1_sel:BYTE_0
	v_readlane_b32 s0, v254, 47
	v_and_b32_e32 v3, 32, v3
	v_bfe_i32 v15, v1, 0, 16
	v_readlane_b32 s1, v254, 48
	s_add_u32 s22, s29, s0
	v_add_lshl_u32 v1, v3, v15, 1
	s_addc_u32 s23, s30, s1
	s_add_i32 s34, s31, 0
	v_lshl_add_u32 v4, v2, 11, v1
	s_add_i32 m0, s34, 0x10000
	v_readlane_b32 s0, v254, 43
	global_load_lds_dwordx4 v4, s[22:23]
	s_add_i32 m0, s34, 0x12000
	v_readlane_b32 s1, v254, 44
	s_add_u32 s6, s27, s0
	v_lshl_add_u32 v194, v0, 11, v1
	global_load_lds_dwordx4 v190, s[22:23]
	s_addc_u32 s7, s28, s1
	s_mov_b32 m0, s34
	s_add_i32 s35, s34, 0x2000
	global_load_lds_dwordx4 v194, s[6:7]
	s_mov_b32 m0, s35
	s_add_u32 s0, s22, 0x40000
	global_load_lds_dwordx4 v192, s[6:7]
	s_addc_u32 s1, s23, 0
	s_add_i32 m0, s34, 0x14000
	v_mov_b32_e32 v191, v5
	global_load_lds_dwordx4 v4, s[0:1]
	s_add_i32 m0, s34, 0x16000
	v_mov_b32_e32 v195, v5
	global_load_lds_dwordx4 v190, s[0:1]
	s_add_u32 s0, s6, 0x40000
	s_addc_u32 s1, s7, 0
	s_add_i32 s36, s34, 0x4000
	s_mov_b32 m0, s36
	s_add_i32 s37, s34, 0x6000
	global_load_lds_dwordx4 v194, s[0:1]
	s_mov_b32 m0, s37
	v_mov_b32_e32 v193, v5
	global_load_lds_dwordx4 v192, s[0:1]
	v_lshl_add_u64 v[8:9], s[22:23], 0, v[4:5]
	v_lshl_add_u64 v[6:7], s[22:23], 0, v[190:191]
	v_lshl_add_u64 v[2:3], s[6:7], 0, v[194:195]
	s_cmp_lg_u32 s15, 1
	v_lshl_add_u64 v[0:1], s[6:7], 0, v[192:193]
	s_cbranch_scc1 .LBB0_2792
	s_barrier

; __global__ void __launch_bounds__(512, 2) mega_fwd(Params Parg) {
;     extern __shared__ __attribute__((aligned(16))) unsigned char shm[];
	.amdhsa_kernel _Z8mega_fwd6Params
		.amdhsa_group_segment_fixed_size 0
		.amdhsa_private_segment_fixed_size 0
		.amdhsa_kernarg_size 512
		.amdhsa_user_sgpr_count 2
		.amdhsa_user_sgpr_dispatch_ptr 0
		.amdhsa_user_sgpr_queue_ptr 0
		.amdhsa_user_sgpr_kernarg_segment_ptr 1
		.amdhsa_user_sgpr_dispatch_id 0
		.amdhsa_user_sgpr_kernarg_preload_length 0
		.amdhsa_user_sgpr_kernarg_preload_offset 0
		.amdhsa_user_sgpr_private_segment_size 0
		.amdhsa_uses_dynamic_stack 0
		.amdhsa_enable_private_segment 0
		.amdhsa_system_sgpr_workgroup_id_x 1
		.amdhsa_system_sgpr_workgroup_id_y 0
		.amdhsa_system_sgpr_workgroup_id_z 0
		.amdhsa_system_sgpr_workgroup_info 0
		.amdhsa_system_vgpr_workitem_id 2
		.amdhsa_next_free_vgpr 256
		.amdhsa_next_free_sgpr 100
		.amdhsa_accum_offset 256
		.amdhsa_reserve_vcc 1
		.amdhsa_float_round_mode_32 0
		.amdhsa_float_round_mode_16_64 0
		.amdhsa_float_denorm_mode_32 3
		.amdhsa_float_denorm_mode_16_64 3
		.amdhsa_dx10_clamp 1
		.amdhsa_ieee_mode 1
		.amdhsa_fp16_overflow 0
		.amdhsa_tg_split 0
		.amdhsa_exception_fp_ieee_invalid_op 0
		.amdhsa_exception_fp_denorm_src 0
		.amdhsa_exception_fp_ieee_div_zero 0
		.amdhsa_exception_fp_ieee_overflow 0
		.amdhsa_exception_fp_ieee_underflow 0
		.amdhsa_exception_fp_ieee_inexact 0
		.amdhsa_exception_int_div_zero 0
	.end_amdhsa_kernel

; __global__ void __launch_bounds__(512, 2) mega_fwd(Params Parg) {
;     extern __shared__ __attribute__((aligned(16))) unsigned char shm[];
amdhsa.kernels:
  - .agpr_count:     0
    .args:
      - .offset:         0
        .size:           256
        .value_kind:     by_value
      - .offset:         256
        .size:           4
        .value_kind:     hidden_block_count_x
      - .offset:         260
        .size:           4
        .value_kind:     hidden_block_count_y
      - .offset:         264
        .size:           4
        .value_kind:     hidden_block_count_z
      - .offset:         268
        .size:           2
        .value_kind:     hidden_group_size_x
      - .offset:         270
        .size:           2
        .value_kind:     hidden_group_size_y
      - .offset:         272
        .size:           2
        .value_kind:     hidden_group_size_z
      - .offset:         274
        .size:           2
        .value_kind:     hidden_remainder_x
      - .offset:         276
        .size:           2
        .value_kind:     hidden_remainder_y
      - .offset:         278
        .size:           2
        .value_kind:     hidden_remainder_z
      - .offset:         296
        .size:           8
        .value_kind:     hidden_global_offset_x
      - .offset:         304
        .size:           8
        .value_kind:     hidden_global_offset_y
      - .offset:         312
        .size:           8
        .value_kind:     hidden_global_offset_z
      - .offset:         320
        .size:           2
        .value_kind:     hidden_grid_dims
      - .offset:         344
        .size:           8
        .value_kind:     hidden_multigrid_sync_arg
      - .offset:         376
        .size:           4
        .value_kind:     hidden_dynamic_lds_size
    .group_segment_fixed_size: 0
    .kernarg_segment_align: 8
    .kernarg_segment_size: 512
    .language:       OpenCL C
    .language_version:
      - 2
      - 0
    .max_flat_workgroup_size: 512
    .name:           _Z8mega_fwd6Params
    .private_segment_fixed_size: 0
    .sgpr_count:     106
    .sgpr_spill_count: 98
    .symbol:         _Z8mega_fwd6Params.kd
    .uniform_work_group_size: 1
    .uses_dynamic_stack: false
    .vgpr_count:     256
    .vgpr_spill_count: 0
    .wavefront_size: 64
